# layer-0 mix: context attention/retout/hyena-ctx items moved from blocks>=256 to blocks<192 as third item
# speedup vs baseline: 1.0828x; 1.0044x over previous
.LBB0_17:
	s_and_b64 vcc, exec, s[84:85]
	v_writelane_b32 v253, s3, 14
	s_cbranch_vccz .LBB0_23
	s_mul_hi_u32 s0, s3, 0xaaaaaaab
	s_lshr_b32 s2, s0, 2
	s_mul_i32 s8, s2, s81
	s_add_i32 s8, s8, s88
	s_cmpk_lt_i32 s8, 0x100
	s_cselect_b64 s[0:1], -1, 0
	s_cmpk_gt_i32 s8, 0xff
	s_cbranch_scc1 .LBB0_105
	s_mul_i32 s9, s2, -6
	s_add_i32 s9, s9, s3
	s_cmp_lt_i32 s9, 1
	s_cbranch_scc1 .LBB0_106
	s_cmp_eq_u32 s9, 1
	s_mov_b64 s[4:5], -1
	s_cbranch_scc0 .LBB0_22
	s_add_i32 s2, s8, 0xffffff80
	s_cmp_lt_u32 s2, 0x80
	v_readlane_b32 s4, v252, 46
	s_cselect_b64 s[2:3], -1, 0
	v_readlane_b32 s5, v252, 47
	s_and_b64 s[2:3], s[4:5], s[2:3]
	s_and_b64 s[2:3], s[2:3], exec
	s_cselect_b32 s3, 2, -1
	s_cselect_b32 s2, s8, 0
	s_mov_b64 s[4:5], 0

.LBB0_108:
	s_andn2_b64 vcc, exec, s[4:5]
	s_cbranch_vccnz .LBB0_614
	s_and_b32 s2, s9, -2
	s_cmp_lg_u32 s2, 2
	s_mov_b64 s[4:5], -1
	s_cbranch_scc0 .LBB0_611
	s_cmp_lg_u32 s9, 4
	s_cbranch_scc0 .LBB0_113
	s_and_b32 s2, s8, 0xffffffc0
	s_cmp_lg_u32 s2, 0x7000
	v_readlane_b32 s4, v253, 8
	s_cselect_b64 s[2:3], -1, 0
	v_readlane_b32 s5, v253, 9
	s_or_b64 s[2:3], s[4:5], s[2:3]
	s_and_b64 vcc, exec, s[2:3]
	s_cbranch_vccnz .LBB0_609
	s_sub_i32 s2, s8, 64
	s_lshr_b32 s2, s2, 1
	s_mul_i32 s2, s2, 18
	s_and_b32 s3, s8, 1
	s_or_b32 s2, s2, s3
	s_add_i32 s2, s2, 16
	s_mov_b32 s3, 3
	s_mov_b64 s[4:5], 0

.LBB0_114:
	s_cmp_gt_i32 s8, -1
	v_readlane_b32 s6, v253, 8
	s_cselect_b64 s[2:3], -1, 0
	v_readlane_b32 s7, v253, 9
	s_or_b64 s[2:3], s[6:7], s[2:3]
	s_mov_b64 s[4:5], -1
	s_and_b64 vcc, exec, s[2:3]
	s_cbranch_vccz .LBB0_116
	s_and_b32 s2, s8, 0xffffffc0
	s_cmpk_eq_i32 s2, 0x80
	v_readlane_b32 s4, v252, 46
	s_cselect_b64 s[2:3], -1, 0
	v_readlane_b32 s5, v252, 47
	s_and_b64 s[2:3], s[4:5], s[2:3]
	s_sub_i32 s4, s8, 64
	s_and_b64 s[2:3], s[2:3], exec
	s_cselect_b32 s3, 2, -1
	s_cselect_b32 s2, s4, 0
	s_mov_b64 s[4:5], 0

.LBB0_621:
	s_cmp_lg_u32 s2, 2
	s_cbranch_scc1 .Lg1_none
	v_readlane_b32 s4, v252, 50
	s_cmp_lg_u32 s4, 0
	s_cbranch_scc1 .Lg1_none
	s_cmpk_lt_i32 s73, 64
	s_cbranch_scc0 .Lg1_b
	s_add_i32 s2, s73, 0x200
	s_mov_b32 s3, 1
	s_branch .Lg1_go
.Lg1_b:
	s_cmpk_lt_i32 s73, 0x80
	s_cbranch_scc0 .Lg1_c
	s_sub_i32 s2, s73, 64
	s_mov_b32 s3, 2
	s_branch .Lg1_go
.Lg1_c:
	s_cmpk_lt_i32 s73, 0xc0
	s_cbranch_scc0 .Lg1_none
	s_sub_i32 s2, s73, 0x80
	s_lshr_b32 s4, s2, 1
	s_mul_i32 s4, s4, 18
	s_and_b32 s2, s2, 1
	s_or_b32 s2, s4, s2
	s_add_i32 s2, s2, 16
	s_mov_b32 s3, 3
.Lg1_go:
	s_mov_b32 s10, 0
	s_branch .LBB0_25
.Lg1_none:
	s_mov_b32 s10, 17
	s_mov_b32 s2, 0
	s_mov_b32 s3, -1
	s_and_b64 vcc, exec, s[0:1]
	s_cbranch_vccnz .LBB0_25
